# grid barrier: the last XCD leader releases first and invalidates its own L1 afterwards; other leaders invalidate before polling
# baseline (speedup 1.0000x reference)
.LBB0_588:
	s_or_b64 exec, exec, s[4:5]
	s_waitcnt vmcnt(0)
	v_readfirstlane_b32 s2, v3
	v_sub_u32_e32 v4, 0, v2
	s_mov_b64 s[4:5], -1
	v_add_u32_e32 v3, s2, v0
	v_cvt_f32_u32_e32 v0, v2
	v_readlane_b32 s2, v215, 26
	v_readlane_b32 s3, v215, 27
	v_rcp_iflag_f32_e32 v0, v0
	s_nop 0
	v_mul_f32_e32 v0, 0x4f7ffffe, v0
	v_cvt_u32_f32_e32 v0, v0
	v_mul_lo_u32 v4, v4, v0
	v_mul_hi_u32 v4, v0, v4
	v_add_u32_e32 v0, v0, v4
	v_mul_hi_u32 v0, v3, v0
	v_mul_lo_u32 v4, v0, v2
	v_sub_u32_e32 v4, v3, v4
	v_cmp_ge_u32_e32 vcc, v4, v2
	v_add_u32_e32 v5, 1, v0
	v_add_u32_e32 v3, 1, v3
	v_cndmask_b32_e32 v0, v0, v5, vcc
	v_sub_u32_e32 v5, v4, v2
	v_cndmask_b32_e32 v4, v4, v5, vcc
	v_cmp_ge_u32_e32 vcc, v4, v2
	v_add_u32_e32 v4, 1, v0
	s_nop 0
	v_cndmask_b32_e32 v0, v0, v4, vcc
	v_mul_lo_u32 v4, v2, v0
	v_add_u32_e32 v2, v4, v2
	v_cmp_ne_u32_e32 vcc, v3, v2
	v_mov_b64_e32 v[2:3], s[2:3]
	s_mov_b32 s16, 0
	s_and_saveexec_b64 s[2:3], vcc
	s_cbranch_execz .LBB0_600
	s_mov_b32 s16, 1
	buffer_inv sc1
	v_readlane_b32 s4, v215, 26
	v_readlane_b32 s5, v215, 27
	s_mov_b64 s[6:7], 0
	s_nop 3
	global_load_dword v2, v1, s[4:5] sc1
	s_waitcnt vmcnt(0)
	v_cmp_eq_u32_e32 vcc, v2, v0
	s_and_saveexec_b64 s[4:5], vcc
	s_cbranch_execz .LBB0_599
	s_mov_b32 s16, 1
	s_branch .LBB0_592

.LBB0_600:
	s_or_b64 exec, exec, s[2:3]
	s_and_saveexec_b64 s[2:3], s[4:5]
	s_cbranch_execz .LBB0_602
	global_atomic_add v[2:3], v146, off
	s_cmp_lg_u32 s16, 0
	s_cbranch_scc1 .Lbar_notlast
	v_readlane_b32 s10, v215, 26
	v_readlane_b32 s11, v215, 27
	s_nop 1
	s_sub_u32 s10, s10, 0x1100
	s_subb_u32 s11, s11, 0
	s_nop 4
	global_atomic_add v1, v146, s[10:11]
	global_atomic_add v1, v146, s[10:11] offset:256
	global_atomic_add v1, v146, s[10:11] offset:512
	global_atomic_add v1, v146, s[10:11] offset:768
	global_atomic_add v1, v146, s[10:11] offset:1024
	global_atomic_add v1, v146, s[10:11] offset:1280
	global_atomic_add v1, v146, s[10:11] offset:1536
	global_atomic_add v1, v146, s[10:11] offset:1792
	global_atomic_add v1, v146, s[10:11] offset:2048
	global_atomic_add v1, v146, s[10:11] offset:2304
	global_atomic_add v1, v146, s[10:11] offset:2560
	global_atomic_add v1, v146, s[10:11] offset:2816
	global_atomic_add v1, v146, s[10:11] offset:3072
	global_atomic_add v1, v146, s[10:11] offset:3328
	global_atomic_add v1, v146, s[10:11] offset:3584
	global_atomic_add v1, v146, s[10:11] offset:3840
	buffer_inv sc1
	s_waitcnt vmcnt(0)
